# decode: next page's table entry fetched one page ahead and next latent page touched into L2 behind the last head of the current page
# baseline (speedup 1.0000x reference)
.LBB0_1540:
	s_add_i32 s0, s89, s97
	s_ashr_i32 s1, s0, 31
	v_readlane_b32 s8, v252, 12
	s_lshl_b64 s[0:1], s[0:1], 2
	v_readlane_b32 s12, v252, 16
	v_readlane_b32 s13, v252, 17
	s_add_u32 s0, s12, s0
	s_addc_u32 s1, s13, s1
	global_load_dword v2, v7, s[0:1]
	s_cmp_lt_u32 s97, 31
	s_cselect_b32 s99, 4, 0
	v_mov_b32_e32 v245, s99
	global_load_dword v245, v245, s[0:1]
	v_readlane_b32 s9, v252, 13
	v_readlane_b32 s10, v252, 14
	v_readlane_b32 s11, v252, 15
	v_readlane_b32 s14, v252, 18
	v_readlane_b32 s15, v252, 19
	v_readlane_b32 s8, v252, 58
	v_readlane_b32 s9, v252, 59
	v_readlane_b32 s12, v252, 62
	v_readlane_b32 s13, v252, 63
	s_mov_b64 s[8:9], s[12:13]
	v_mov_b32_e32 v174, v228
	s_waitcnt lgkmcnt(0)
	s_barrier
	s_mov_b32 s2, 0x8000
	v_lshlrev_b32_e32 v6, 4, v174
	v_readlane_b32 s14, v251, 0
	v_readlane_b32 s15, v251, 1
	v_readlane_b32 s16, v251, 2
	v_readlane_b32 s17, v251, 3
	v_readlane_b32 s18, v251, 4
	v_readlane_b32 s19, v251, 5
	v_readlane_b32 s20, v251, 6
	v_readlane_b32 s21, v251, 7
	v_readlane_b32 s22, v251, 8
	v_readlane_b32 s23, v251, 9
	s_mov_b64 s[12:13], s[16:17]
	v_readlane_b32 s10, v252, 60
	v_readlane_b32 s11, v252, 61
	s_mov_b64 s[14:15], s[18:19]
	s_mov_b64 s[16:17], s[20:21]
	s_mov_b64 s[18:19], s[22:23]
	s_waitcnt vmcnt(0)
	v_readfirstlane_b32 s0, v2
	v_readfirstlane_b32 s98, v245
	s_ashr_i32 s1, s0, 31
	s_lshl_b64 s[6:7], s[0:1], 17
	s_add_u32 s6, s8, s6
	s_addc_u32 s7, s9, s7
	v_readlane_b32 s20, v253, 50
	v_readlane_b32 s21, v253, 51
	v_lshlrev_b64 v[176:177], 14, s[0:1]
	v_lshl_add_u64 v[176:177], v[226:227], 0, v[176:177]
	s_and_b64 vcc, exec, s[20:21]
	s_cbranch_vccz .Lkp_skip
	global_load_dwordx4 v[178:181], v[176:177], off
	global_load_dwordx4 v[182:185], v[176:177], off offset:16
	global_load_dwordx4 v[186:189], v[176:177], off offset:64
	global_load_dwordx4 v[190:193], v[176:177], off offset:80

.LBB0_1630:
	s_cmp_lt_u32 s97, 31
	s_cbranch_scc0 .Lpf_skip
	v_readlane_b32 s100, v252, 62
	v_readlane_b32 s101, v252, 63
	s_mov_b32 s99, 0
	s_lshl_b64 s[98:99], s[98:99], 17
	s_add_u32 s100, s100, s98
	s_addc_u32 s101, s101, s99
	v_lshrrev_b32_e32 v156, 6, v228
	v_lshlrev_b32_e32 v156, 13, v156
	v_lshl_add_u32 v156, v228, 7, v156
	v_add_u32_e32 v157, 0x2000, v156
	global_load_dword v154, v156, s[100:101]
	global_load_dword v155, v157, s[100:101]

	.amdhsa_kernel _Z6mega108MegaArgs
		.amdhsa_group_segment_fixed_size 0
		.amdhsa_private_segment_fixed_size 0
		.amdhsa_kernarg_size 1336
		.amdhsa_user_sgpr_count 2
		.amdhsa_user_sgpr_dispatch_ptr 0
		.amdhsa_user_sgpr_queue_ptr 0
		.amdhsa_user_sgpr_kernarg_segment_ptr 1
		.amdhsa_user_sgpr_dispatch_id 0
		.amdhsa_user_sgpr_kernarg_preload_length 0
		.amdhsa_user_sgpr_kernarg_preload_offset 0
		.amdhsa_user_sgpr_private_segment_size 0
		.amdhsa_uses_dynamic_stack 0
		.amdhsa_enable_private_segment 0
		.amdhsa_system_sgpr_workgroup_id_x 1
		.amdhsa_system_sgpr_workgroup_id_y 0
		.amdhsa_system_sgpr_workgroup_id_z 0
		.amdhsa_system_sgpr_workgroup_info 0
		.amdhsa_system_vgpr_workitem_id 0
		.amdhsa_next_free_vgpr 254
		.amdhsa_next_free_sgpr 102
		.amdhsa_accum_offset 256
		.amdhsa_reserve_vcc 1
		.amdhsa_float_round_mode_32 0
		.amdhsa_float_round_mode_16_64 0
		.amdhsa_float_denorm_mode_32 3
		.amdhsa_float_denorm_mode_16_64 3
		.amdhsa_dx10_clamp 1
		.amdhsa_ieee_mode 1
		.amdhsa_fp16_overflow 0
		.amdhsa_tg_split 0
		.amdhsa_exception_fp_ieee_invalid_op 0
		.amdhsa_exception_fp_denorm_src 0
		.amdhsa_exception_fp_ieee_div_zero 0
		.amdhsa_exception_fp_ieee_overflow 0
		.amdhsa_exception_fp_ieee_underflow 0
		.amdhsa_exception_fp_ieee_inexact 0
		.amdhsa_exception_int_div_zero 0
	.end_amdhsa_kernel

amdhsa.kernels:
  - .agpr_count:     0
    .args:
      - .offset:         0
        .size:           1080
        .value_kind:     by_value
      - .offset:         1080
        .size:           4
        .value_kind:     hidden_block_count_x
      - .offset:         1084
        .size:           4
        .value_kind:     hidden_block_count_y
      - .offset:         1088
        .size:           4
        .value_kind:     hidden_block_count_z
      - .offset:         1092
        .size:           2
        .value_kind:     hidden_group_size_x
      - .offset:         1094
        .size:           2
        .value_kind:     hidden_group_size_y
      - .offset:         1096
        .size:           2
        .value_kind:     hidden_group_size_z
      - .offset:         1098
        .size:           2
        .value_kind:     hidden_remainder_x
      - .offset:         1100
        .size:           2
        .value_kind:     hidden_remainder_y
      - .offset:         1102
        .size:           2
        .value_kind:     hidden_remainder_z
      - .offset:         1120
        .size:           8
        .value_kind:     hidden_global_offset_x
      - .offset:         1128
        .size:           8
        .value_kind:     hidden_global_offset_y
      - .offset:         1136
        .size:           8
        .value_kind:     hidden_global_offset_z
      - .offset:         1144
        .size:           2
        .value_kind:     hidden_grid_dims
      - .offset:         1200
        .size:           4
        .value_kind:     hidden_dynamic_lds_size
    .group_segment_fixed_size: 0
    .kernarg_segment_align: 8
    .kernarg_segment_size: 1336
    .language:       OpenCL C
    .language_version:
      - 2
      - 0
    .max_flat_workgroup_size: 512
    .name:           _Z6mega108MegaArgs
    .private_segment_fixed_size: 0
    .sgpr_count:     108
    .sgpr_spill_count: 328
    .symbol:         _Z6mega108MegaArgs.kd
    .uniform_work_group_size: 1
    .uses_dynamic_stack: false
    .vgpr_count:     254
    .vgpr_spill_count: 0
    .wavefront_size: 64
